# GEMM k-loops: counted LDS wait (lgkmcnt(8) before the first 16 MFMAs, drain before the 17th)
# speedup vs baseline: 1.0242x; 1.0041x over previous
.LBB0_155:
	ds_read_b128 v[82:85], v115 offset:32768
	ds_read_b128 v[86:89], v115 offset:34816
	ds_read_b128 v[90:93], v115 offset:36864
	ds_read_b128 v[94:97], v115 offset:38912
	ds_read_b128 v[120:123], v116 offset:49152
	ds_read_b128 v[124:127], v116 offset:51200
	ds_read_b128 v[128:131], v116 offset:53248
	ds_read_b128 v[132:135], v116 offset:55296
	ds_read_b128 v[136:139], v117 offset:32768
	ds_read_b128 v[140:143], v117 offset:34816
	ds_read_b128 v[144:147], v117 offset:36864
	ds_read_b128 v[148:151], v117 offset:38912
	ds_read_b128 v[152:155], v118 offset:49152
	ds_read_b128 v[156:159], v118 offset:51200
	ds_read_b128 v[160:163], v118 offset:53248
	ds_read_b128 v[164:167], v118 offset:55296
	s_add_i32 s7, s7, 2
	s_waitcnt lgkmcnt(8)
	v_mfma_f32_16x16x32_f16 v[0:3], v[120:123], v[82:85], v[0:3]
	v_mfma_f32_16x16x32_f16 v[4:7], v[124:127], v[82:85], v[4:7]
	v_mfma_f32_16x16x32_f16 v[8:11], v[128:131], v[82:85], v[8:11]
	v_mfma_f32_16x16x32_f16 v[12:15], v[132:135], v[82:85], v[12:15]
	v_mfma_f32_16x16x32_f16 v[16:19], v[120:123], v[86:89], v[16:19]
	v_mfma_f32_16x16x32_f16 v[20:23], v[124:127], v[86:89], v[20:23]
	v_mfma_f32_16x16x32_f16 v[24:27], v[128:131], v[86:89], v[24:27]
	v_mfma_f32_16x16x32_f16 v[28:31], v[132:135], v[86:89], v[28:31]
	v_mfma_f32_16x16x32_f16 v[82:85], v[120:123], v[90:93], v[32:35]
	v_mfma_f32_16x16x32_f16 v[86:89], v[124:127], v[90:93], v[36:39]
	v_mfma_f32_16x16x32_f16 v[168:171], v[128:131], v[90:93], v[40:43]
	v_mfma_f32_16x16x32_f16 v[90:93], v[132:135], v[90:93], v[44:47]
	v_mfma_f32_16x16x32_f16 v[120:123], v[120:123], v[94:97], v[48:51]
	v_mfma_f32_16x16x32_f16 v[124:127], v[124:127], v[94:97], v[52:55]
	v_mfma_f32_16x16x32_f16 v[128:131], v[128:131], v[94:97], v[56:59]
	v_mfma_f32_16x16x32_f16 v[94:97], v[132:135], v[94:97], v[60:63]
	s_waitcnt lgkmcnt(0)
	v_mfma_f32_16x16x32_f16 v[60:63], v[152:155], v[136:139], v[0:3]
	v_mfma_f32_16x16x32_f16 v[56:59], v[156:159], v[136:139], v[4:7]
	v_mfma_f32_16x16x32_f16 v[52:55], v[160:163], v[136:139], v[8:11]
	v_mfma_f32_16x16x32_f16 v[48:51], v[164:167], v[136:139], v[12:15]
	v_mfma_f32_16x16x32_f16 v[44:47], v[152:155], v[140:143], v[16:19]
	v_mfma_f32_16x16x32_f16 v[40:43], v[156:159], v[140:143], v[20:23]
	v_mfma_f32_16x16x32_f16 v[36:39], v[160:163], v[140:143], v[24:27]
	v_mfma_f32_16x16x32_f16 v[32:35], v[164:167], v[140:143], v[28:31]
	v_mfma_f32_16x16x32_f16 v[28:31], v[152:155], v[144:147], v[82:85]
	v_mfma_f32_16x16x32_f16 v[24:27], v[156:159], v[144:147], v[86:89]
	v_mfma_f32_16x16x32_f16 v[20:23], v[160:163], v[144:147], v[168:171]
	v_mfma_f32_16x16x32_f16 v[16:19], v[164:167], v[144:147], v[90:93]
	v_mfma_f32_16x16x32_f16 v[12:15], v[152:155], v[148:151], v[120:123]
	v_mfma_f32_16x16x32_f16 v[8:11], v[156:159], v[148:151], v[124:127]
	v_mfma_f32_16x16x32_f16 v[4:7], v[160:163], v[148:151], v[128:131]
	v_mfma_f32_16x16x32_f16 v[0:3], v[164:167], v[148:151], v[94:97]
	s_andn2_b64 vcc, exec, s[12:13]
	s_cbranch_vccz .LBB0_153
.LBB0_156:
	s_waitcnt vmcnt(0)
	s_waitcnt vmcnt(0) lgkmcnt(0)
	s_barrier
	s_add_i32 m0, s100, 0x8000
	s_nop 0
	global_load_lds_dwordx4 v74, s[10:11]
	s_add_i32 m0, s100, 0x9000
	s_nop 0
	global_load_lds_dwordx4 v76, s[10:11]
	s_add_i32 m0, s100, 0xa000
	s_nop 0
	global_load_lds_dwordx4 v78, s[10:11]
	s_add_i32 m0, s100, 0xb000
	s_nop 0
	global_load_lds_dwordx4 v80, s[10:11]
	s_add_i32 m0, s100, 0xc000
	s_nop 0
	global_load_lds_dwordx4 v66, s[98:99]
	s_add_i32 m0, s100, 0xd000
	s_nop 0
	global_load_lds_dwordx4 v68, s[98:99]
	s_add_i32 m0, s100, 0xe000
	s_nop 0
	global_load_lds_dwordx4 v70, s[98:99]
	s_add_i32 m0, s100, 0xf000
	s_nop 0
	global_load_lds_dwordx4 v72, s[98:99]
	s_add_u32 s10, s10, 0x80
	s_addc_u32 s11, s11, 0
	s_add_u32 s98, s98, 0x80
	s_addc_u32 s99, s99, 0
	ds_read_b128 v[120:123], v115
	ds_read_b128 v[124:127], v115 offset:2048
	ds_read_b128 v[128:131], v115 offset:4096
	ds_read_b128 v[132:135], v115 offset:6144
	ds_read_b128 v[136:139], v116 offset:16384
	ds_read_b128 v[140:143], v116 offset:18432
	ds_read_b128 v[144:147], v116 offset:20480
	ds_read_b128 v[148:151], v116 offset:22528
	ds_read_b128 v[152:155], v117
	ds_read_b128 v[156:159], v117 offset:2048
	ds_read_b128 v[160:163], v117 offset:4096
	ds_read_b128 v[164:167], v117 offset:6144
	ds_read_b128 v[168:171], v118 offset:16384
	ds_read_b128 v[176:179], v118 offset:18432
	ds_read_b128 v[180:183], v118 offset:20480
	ds_read_b128 v[184:187], v118 offset:22528
	s_waitcnt lgkmcnt(8)
	v_mfma_f32_16x16x32_f16 v[60:63], v[136:139], v[120:123], v[60:63]
	v_mfma_f32_16x16x32_f16 v[56:59], v[140:143], v[120:123], v[56:59]
	v_mfma_f32_16x16x32_f16 v[52:55], v[144:147], v[120:123], v[52:55]
	v_mfma_f32_16x16x32_f16 v[48:51], v[148:151], v[120:123], v[48:51]
	v_mfma_f32_16x16x32_f16 v[44:47], v[136:139], v[124:127], v[44:47]
	v_mfma_f32_16x16x32_f16 v[40:43], v[140:143], v[124:127], v[40:43]
	v_mfma_f32_16x16x32_f16 v[36:39], v[144:147], v[124:127], v[36:39]
	v_mfma_f32_16x16x32_f16 v[32:35], v[148:151], v[124:127], v[32:35]
	v_mfma_f32_16x16x32_f16 v[120:123], v[136:139], v[128:131], v[28:31]
	v_mfma_f32_16x16x32_f16 v[124:127], v[140:143], v[128:131], v[24:27]
	v_mfma_f32_16x16x32_f16 v[188:191], v[144:147], v[128:131], v[20:23]
	v_mfma_f32_16x16x32_f16 v[128:131], v[148:151], v[128:131], v[16:19]
	v_mfma_f32_16x16x32_f16 v[136:139], v[136:139], v[132:135], v[12:15]
	v_mfma_f32_16x16x32_f16 v[140:143], v[140:143], v[132:135], v[8:11]
	v_mfma_f32_16x16x32_f16 v[144:147], v[144:147], v[132:135], v[4:7]
	v_mfma_f32_16x16x32_f16 v[132:135], v[148:151], v[132:135], v[0:3]
	s_waitcnt lgkmcnt(0)
	v_mfma_f32_16x16x32_f16 v[0:3], v[168:171], v[152:155], v[60:63]
	v_mfma_f32_16x16x32_f16 v[4:7], v[176:179], v[152:155], v[56:59]
	v_mfma_f32_16x16x32_f16 v[8:11], v[180:183], v[152:155], v[52:55]
	v_mfma_f32_16x16x32_f16 v[12:15], v[184:187], v[152:155], v[48:51]
	v_mfma_f32_16x16x32_f16 v[16:19], v[168:171], v[156:159], v[44:47]
	v_mfma_f32_16x16x32_f16 v[20:23], v[176:179], v[156:159], v[40:43]
	v_mfma_f32_16x16x32_f16 v[24:27], v[180:183], v[156:159], v[36:39]
	v_mfma_f32_16x16x32_f16 v[28:31], v[184:187], v[156:159], v[32:35]
	v_mfma_f32_16x16x32_f16 v[32:35], v[168:171], v[160:163], v[120:123]
	v_mfma_f32_16x16x32_f16 v[36:39], v[176:179], v[160:163], v[124:127]
	v_mfma_f32_16x16x32_f16 v[40:43], v[180:183], v[160:163], v[188:191]
	v_mfma_f32_16x16x32_f16 v[44:47], v[184:187], v[160:163], v[128:131]
	v_mfma_f32_16x16x32_f16 v[48:51], v[168:171], v[164:167], v[136:139]
	v_mfma_f32_16x16x32_f16 v[52:55], v[176:179], v[164:167], v[140:143]
	v_mfma_f32_16x16x32_f16 v[56:59], v[180:183], v[164:167], v[144:147]
	v_mfma_f32_16x16x32_f16 v[60:63], v[184:187], v[164:167], v[132:135]
	s_waitcnt vmcnt(0)
	s_cmp_gt_u32 s7, 13
	s_cselect_b64 s[12:13], -1, 0
	s_and_b64 vcc, exec, s[12:13]
	s_waitcnt vmcnt(0)
	s_barrier
	s_cbranch_vccnz .LBB0_155
	s_mov_b32 m0, s100
	s_nop 0
	global_load_lds_dwordx4 v74, s[10:11]
	s_add_i32 m0, s100, 0x1000
	s_nop 0
	global_load_lds_dwordx4 v76, s[10:11]
	s_add_i32 m0, s100, 0x2000
	s_nop 0
	global_load_lds_dwordx4 v78, s[10:11]
	s_add_i32 m0, s100, 0x3000
	s_nop 0
	global_load_lds_dwordx4 v80, s[10:11]
	s_add_i32 m0, s100, 0x4000
	s_nop 0
	global_load_lds_dwordx4 v66, s[98:99]
	s_add_i32 m0, s100, 0x5000
	s_nop 0
	global_load_lds_dwordx4 v68, s[98:99]
	s_add_i32 m0, s100, 0x6000
	s_nop 0
	global_load_lds_dwordx4 v70, s[98:99]
	s_add_i32 m0, s100, 0x7000
	s_nop 0
	global_load_lds_dwordx4 v72, s[98:99]
	s_add_u32 s10, s10, 0x80
	s_addc_u32 s11, s11, 0
	s_add_u32 s98, s98, 0x80
	s_addc_u32 s99, s99, 0
	s_branch .LBB0_155

.LBB0_609:
	ds_read_b128 v[82:85], v115 offset:32768
	ds_read_b128 v[86:89], v115 offset:34816
	ds_read_b128 v[90:93], v115 offset:36864
	ds_read_b128 v[94:97], v115 offset:38912
	ds_read_b128 v[120:123], v116 offset:49152
	ds_read_b128 v[124:127], v116 offset:51200
	ds_read_b128 v[128:131], v116 offset:53248
	ds_read_b128 v[132:135], v116 offset:55296
	ds_read_b128 v[136:139], v117 offset:32768
	ds_read_b128 v[140:143], v117 offset:34816
	ds_read_b128 v[144:147], v117 offset:36864
	ds_read_b128 v[148:151], v117 offset:38912
	ds_read_b128 v[152:155], v118 offset:49152
	ds_read_b128 v[156:159], v118 offset:51200
	ds_read_b128 v[160:163], v118 offset:53248
	ds_read_b128 v[164:167], v118 offset:55296
	s_add_i32 s11, s11, 2
	s_waitcnt lgkmcnt(8)
	v_mfma_f32_16x16x32_f16 v[0:3], v[120:123], v[82:85], v[0:3]
	v_mfma_f32_16x16x32_f16 v[4:7], v[124:127], v[82:85], v[4:7]
	v_mfma_f32_16x16x32_f16 v[8:11], v[128:131], v[82:85], v[8:11]
	v_mfma_f32_16x16x32_f16 v[12:15], v[132:135], v[82:85], v[12:15]
	v_mfma_f32_16x16x32_f16 v[16:19], v[120:123], v[86:89], v[16:19]
	v_mfma_f32_16x16x32_f16 v[20:23], v[124:127], v[86:89], v[20:23]
	v_mfma_f32_16x16x32_f16 v[24:27], v[128:131], v[86:89], v[24:27]
	v_mfma_f32_16x16x32_f16 v[28:31], v[132:135], v[86:89], v[28:31]
	v_mfma_f32_16x16x32_f16 v[82:85], v[120:123], v[90:93], v[32:35]
	v_mfma_f32_16x16x32_f16 v[86:89], v[124:127], v[90:93], v[36:39]
	v_mfma_f32_16x16x32_f16 v[168:171], v[128:131], v[90:93], v[40:43]
	v_mfma_f32_16x16x32_f16 v[90:93], v[132:135], v[90:93], v[44:47]
	v_mfma_f32_16x16x32_f16 v[120:123], v[120:123], v[94:97], v[48:51]
	v_mfma_f32_16x16x32_f16 v[124:127], v[124:127], v[94:97], v[52:55]
	v_mfma_f32_16x16x32_f16 v[128:131], v[128:131], v[94:97], v[56:59]
	v_mfma_f32_16x16x32_f16 v[94:97], v[132:135], v[94:97], v[60:63]
	s_waitcnt lgkmcnt(0)
	v_mfma_f32_16x16x32_f16 v[60:63], v[152:155], v[136:139], v[0:3]
	v_mfma_f32_16x16x32_f16 v[56:59], v[156:159], v[136:139], v[4:7]
	v_mfma_f32_16x16x32_f16 v[52:55], v[160:163], v[136:139], v[8:11]
	v_mfma_f32_16x16x32_f16 v[48:51], v[164:167], v[136:139], v[12:15]
	v_mfma_f32_16x16x32_f16 v[44:47], v[152:155], v[140:143], v[16:19]
	v_mfma_f32_16x16x32_f16 v[40:43], v[156:159], v[140:143], v[20:23]
	v_mfma_f32_16x16x32_f16 v[36:39], v[160:163], v[140:143], v[24:27]
	v_mfma_f32_16x16x32_f16 v[32:35], v[164:167], v[140:143], v[28:31]
	v_mfma_f32_16x16x32_f16 v[28:31], v[152:155], v[144:147], v[82:85]
	v_mfma_f32_16x16x32_f16 v[24:27], v[156:159], v[144:147], v[86:89]
	v_mfma_f32_16x16x32_f16 v[20:23], v[160:163], v[144:147], v[168:171]
	v_mfma_f32_16x16x32_f16 v[16:19], v[164:167], v[144:147], v[90:93]
	v_mfma_f32_16x16x32_f16 v[12:15], v[152:155], v[148:151], v[120:123]
	v_mfma_f32_16x16x32_f16 v[8:11], v[156:159], v[148:151], v[124:127]
	v_mfma_f32_16x16x32_f16 v[4:7], v[160:163], v[148:151], v[128:131]
	v_mfma_f32_16x16x32_f16 v[0:3], v[164:167], v[148:151], v[94:97]
	s_andn2_b64 vcc, exec, s[86:87]
	s_cbranch_vccz .LBB0_607
.LBB0_610:
	s_waitcnt vmcnt(0)
	s_waitcnt vmcnt(0) lgkmcnt(0)
	s_barrier
	s_add_i32 m0, s100, 0x8000
	s_nop 0
	global_load_lds_dwordx4 v66, s[84:85]
	s_add_i32 m0, s100, 0x9000
	s_nop 0
	global_load_lds_dwordx4 v68, s[84:85]
	s_add_i32 m0, s100, 0xa000
	s_nop 0
	global_load_lds_dwordx4 v70, s[84:85]
	s_add_i32 m0, s100, 0xb000
	s_nop 0
	global_load_lds_dwordx4 v72, s[84:85]
	s_add_i32 m0, s100, 0xc000
	s_nop 0
	global_load_lds_dwordx4 v74, s[98:99]
	s_add_i32 m0, s100, 0xd000
	s_nop 0
	global_load_lds_dwordx4 v76, s[98:99]
	s_add_i32 m0, s100, 0xe000
	s_nop 0
	global_load_lds_dwordx4 v78, s[98:99]
	s_add_i32 m0, s100, 0xf000
	s_nop 0
	global_load_lds_dwordx4 v80, s[98:99]
	s_add_u32 s84, s84, 0x80
	s_addc_u32 s85, s85, 0
	s_add_u32 s98, s98, 0x80
	s_addc_u32 s99, s99, 0
	ds_read_b128 v[120:123], v115
	ds_read_b128 v[124:127], v115 offset:2048
	ds_read_b128 v[128:131], v115 offset:4096
	ds_read_b128 v[132:135], v115 offset:6144
	ds_read_b128 v[136:139], v116 offset:16384
	ds_read_b128 v[140:143], v116 offset:18432
	ds_read_b128 v[144:147], v116 offset:20480
	ds_read_b128 v[148:151], v116 offset:22528
	ds_read_b128 v[152:155], v117
	ds_read_b128 v[156:159], v117 offset:2048
	ds_read_b128 v[160:163], v117 offset:4096
	ds_read_b128 v[164:167], v117 offset:6144
	ds_read_b128 v[168:171], v118 offset:16384
	ds_read_b128 v[176:179], v118 offset:18432
	ds_read_b128 v[180:183], v118 offset:20480
	ds_read_b128 v[184:187], v118 offset:22528
	s_waitcnt lgkmcnt(8)
	v_mfma_f32_16x16x32_f16 v[60:63], v[136:139], v[120:123], v[60:63]
	v_mfma_f32_16x16x32_f16 v[56:59], v[140:143], v[120:123], v[56:59]
	v_mfma_f32_16x16x32_f16 v[52:55], v[144:147], v[120:123], v[52:55]
	v_mfma_f32_16x16x32_f16 v[48:51], v[148:151], v[120:123], v[48:51]
	v_mfma_f32_16x16x32_f16 v[44:47], v[136:139], v[124:127], v[44:47]
	v_mfma_f32_16x16x32_f16 v[40:43], v[140:143], v[124:127], v[40:43]
	v_mfma_f32_16x16x32_f16 v[36:39], v[144:147], v[124:127], v[36:39]
	v_mfma_f32_16x16x32_f16 v[32:35], v[148:151], v[124:127], v[32:35]
	v_mfma_f32_16x16x32_f16 v[120:123], v[136:139], v[128:131], v[28:31]
	v_mfma_f32_16x16x32_f16 v[124:127], v[140:143], v[128:131], v[24:27]
	v_mfma_f32_16x16x32_f16 v[188:191], v[144:147], v[128:131], v[20:23]
	v_mfma_f32_16x16x32_f16 v[128:131], v[148:151], v[128:131], v[16:19]
	v_mfma_f32_16x16x32_f16 v[136:139], v[136:139], v[132:135], v[12:15]
	v_mfma_f32_16x16x32_f16 v[140:143], v[140:143], v[132:135], v[8:11]
	v_mfma_f32_16x16x32_f16 v[144:147], v[144:147], v[132:135], v[4:7]
	v_mfma_f32_16x16x32_f16 v[132:135], v[148:151], v[132:135], v[0:3]
	s_waitcnt lgkmcnt(0)
	v_mfma_f32_16x16x32_f16 v[0:3], v[168:171], v[152:155], v[60:63]
	v_mfma_f32_16x16x32_f16 v[4:7], v[176:179], v[152:155], v[56:59]
	v_mfma_f32_16x16x32_f16 v[8:11], v[180:183], v[152:155], v[52:55]
	v_mfma_f32_16x16x32_f16 v[12:15], v[184:187], v[152:155], v[48:51]
	v_mfma_f32_16x16x32_f16 v[16:19], v[168:171], v[156:159], v[44:47]
	v_mfma_f32_16x16x32_f16 v[20:23], v[176:179], v[156:159], v[40:43]
	v_mfma_f32_16x16x32_f16 v[24:27], v[180:183], v[156:159], v[36:39]
	v_mfma_f32_16x16x32_f16 v[28:31], v[184:187], v[156:159], v[32:35]
	v_mfma_f32_16x16x32_f16 v[32:35], v[168:171], v[160:163], v[120:123]
	v_mfma_f32_16x16x32_f16 v[36:39], v[176:179], v[160:163], v[124:127]
	v_mfma_f32_16x16x32_f16 v[40:43], v[180:183], v[160:163], v[188:191]
	v_mfma_f32_16x16x32_f16 v[44:47], v[184:187], v[160:163], v[128:131]
	v_mfma_f32_16x16x32_f16 v[48:51], v[168:171], v[164:167], v[136:139]
	v_mfma_f32_16x16x32_f16 v[52:55], v[176:179], v[164:167], v[140:143]
	v_mfma_f32_16x16x32_f16 v[56:59], v[180:183], v[164:167], v[144:147]
	v_mfma_f32_16x16x32_f16 v[60:63], v[184:187], v[164:167], v[132:135]
	s_waitcnt vmcnt(0)
	s_cmp_gt_u32 s11, 13
	s_cselect_b64 s[86:87], -1, 0
	s_and_b64 vcc, exec, s[86:87]
	s_waitcnt vmcnt(0)
	s_barrier
	s_cbranch_vccnz .LBB0_609
	s_mov_b32 m0, s100
	s_nop 0
	global_load_lds_dwordx4 v66, s[84:85]
	s_add_i32 m0, s100, 0x1000
	s_nop 0
	global_load_lds_dwordx4 v68, s[84:85]
	s_add_i32 m0, s100, 0x2000
	s_nop 0
	global_load_lds_dwordx4 v70, s[84:85]
	s_add_i32 m0, s100, 0x3000
	s_nop 0
	global_load_lds_dwordx4 v72, s[84:85]
	s_add_i32 m0, s100, 0x4000
	s_nop 0
	global_load_lds_dwordx4 v74, s[98:99]
	s_add_i32 m0, s100, 0x5000
	s_nop 0
	global_load_lds_dwordx4 v76, s[98:99]
	s_add_i32 m0, s100, 0x6000
	s_nop 0
	global_load_lds_dwordx4 v78, s[98:99]
	s_add_i32 m0, s100, 0x7000
	s_nop 0
	global_load_lds_dwordx4 v80, s[98:99]
	s_add_u32 s84, s84, 0x80
	s_addc_u32 s85, s85, 0
	s_add_u32 s98, s98, 0x80
	s_addc_u32 s99, s99, 0
	s_branch .LBB0_609

.LBB0_751:
	ds_read_b128 v[82:85], v115 offset:32768
	ds_read_b128 v[86:89], v115 offset:34816
	ds_read_b128 v[90:93], v115 offset:36864
	ds_read_b128 v[94:97], v115 offset:38912
	ds_read_b128 v[120:123], v116 offset:49152
	ds_read_b128 v[124:127], v116 offset:51200
	ds_read_b128 v[128:131], v116 offset:53248
	ds_read_b128 v[132:135], v116 offset:55296
	ds_read_b128 v[136:139], v117 offset:32768
	ds_read_b128 v[140:143], v117 offset:34816
	ds_read_b128 v[144:147], v117 offset:36864
	ds_read_b128 v[148:151], v117 offset:38912
	ds_read_b128 v[152:155], v118 offset:49152
	ds_read_b128 v[156:159], v118 offset:51200
	ds_read_b128 v[160:163], v118 offset:53248
	ds_read_b128 v[164:167], v118 offset:55296
	s_add_i32 s11, s11, 2
	s_waitcnt lgkmcnt(8)
	v_mfma_f32_16x16x32_f16 v[0:3], v[120:123], v[82:85], v[0:3]
	v_mfma_f32_16x16x32_f16 v[4:7], v[124:127], v[82:85], v[4:7]
	v_mfma_f32_16x16x32_f16 v[8:11], v[128:131], v[82:85], v[8:11]
	v_mfma_f32_16x16x32_f16 v[12:15], v[132:135], v[82:85], v[12:15]
	v_mfma_f32_16x16x32_f16 v[16:19], v[120:123], v[86:89], v[16:19]
	v_mfma_f32_16x16x32_f16 v[20:23], v[124:127], v[86:89], v[20:23]
	v_mfma_f32_16x16x32_f16 v[24:27], v[128:131], v[86:89], v[24:27]
	v_mfma_f32_16x16x32_f16 v[28:31], v[132:135], v[86:89], v[28:31]
	v_mfma_f32_16x16x32_f16 v[82:85], v[120:123], v[90:93], v[32:35]
	v_mfma_f32_16x16x32_f16 v[86:89], v[124:127], v[90:93], v[36:39]
	v_mfma_f32_16x16x32_f16 v[168:171], v[128:131], v[90:93], v[40:43]
	v_mfma_f32_16x16x32_f16 v[90:93], v[132:135], v[90:93], v[44:47]
	v_mfma_f32_16x16x32_f16 v[120:123], v[120:123], v[94:97], v[48:51]
	v_mfma_f32_16x16x32_f16 v[124:127], v[124:127], v[94:97], v[52:55]
	v_mfma_f32_16x16x32_f16 v[128:131], v[128:131], v[94:97], v[56:59]
	v_mfma_f32_16x16x32_f16 v[94:97], v[132:135], v[94:97], v[60:63]
	s_waitcnt lgkmcnt(0)
	v_mfma_f32_16x16x32_f16 v[60:63], v[152:155], v[136:139], v[0:3]
	v_mfma_f32_16x16x32_f16 v[56:59], v[156:159], v[136:139], v[4:7]
	v_mfma_f32_16x16x32_f16 v[52:55], v[160:163], v[136:139], v[8:11]
	v_mfma_f32_16x16x32_f16 v[48:51], v[164:167], v[136:139], v[12:15]
	v_mfma_f32_16x16x32_f16 v[44:47], v[152:155], v[140:143], v[16:19]
	v_mfma_f32_16x16x32_f16 v[40:43], v[156:159], v[140:143], v[20:23]
	v_mfma_f32_16x16x32_f16 v[36:39], v[160:163], v[140:143], v[24:27]
	v_mfma_f32_16x16x32_f16 v[32:35], v[164:167], v[140:143], v[28:31]
	v_mfma_f32_16x16x32_f16 v[28:31], v[152:155], v[144:147], v[82:85]
	v_mfma_f32_16x16x32_f16 v[24:27], v[156:159], v[144:147], v[86:89]
	v_mfma_f32_16x16x32_f16 v[20:23], v[160:163], v[144:147], v[168:171]
	v_mfma_f32_16x16x32_f16 v[16:19], v[164:167], v[144:147], v[90:93]
	v_mfma_f32_16x16x32_f16 v[12:15], v[152:155], v[148:151], v[120:123]
	v_mfma_f32_16x16x32_f16 v[8:11], v[156:159], v[148:151], v[124:127]
	v_mfma_f32_16x16x32_f16 v[4:7], v[160:163], v[148:151], v[128:131]
	v_mfma_f32_16x16x32_f16 v[0:3], v[164:167], v[148:151], v[94:97]
	s_andn2_b64 vcc, exec, s[88:89]
	s_cbranch_vccz .LBB0_749
.LBB0_752:
	s_waitcnt vmcnt(0)
	s_waitcnt lgkmcnt(0)
	s_barrier
	s_add_i32 m0, s100, 0x8000
	s_nop 0
	global_load_lds_dwordx4 v66, s[84:85]
	s_add_i32 m0, s100, 0x9000
	s_nop 0
	global_load_lds_dwordx4 v68, s[84:85]
	s_add_i32 m0, s100, 0xa000
	s_nop 0
	global_load_lds_dwordx4 v70, s[84:85]
	s_add_i32 m0, s100, 0xb000
	s_nop 0
	global_load_lds_dwordx4 v72, s[84:85]
	s_add_i32 m0, s100, 0xc000
	s_nop 0
	global_load_lds_dwordx4 v74, s[98:99]
	s_add_i32 m0, s100, 0xd000
	s_nop 0
	global_load_lds_dwordx4 v76, s[98:99]
	s_add_i32 m0, s100, 0xe000
	s_nop 0
	global_load_lds_dwordx4 v78, s[98:99]
	s_add_i32 m0, s100, 0xf000
	s_nop 0
	global_load_lds_dwordx4 v80, s[98:99]
	s_add_u32 s84, s84, 0x80
	s_addc_u32 s85, s85, 0
	s_add_u32 s98, s98, 0x80
	s_addc_u32 s99, s99, 0
	ds_read_b128 v[120:123], v115
	ds_read_b128 v[124:127], v115 offset:2048
	ds_read_b128 v[128:131], v115 offset:4096
	ds_read_b128 v[132:135], v115 offset:6144
	ds_read_b128 v[136:139], v116 offset:16384
	ds_read_b128 v[140:143], v116 offset:18432
	ds_read_b128 v[144:147], v116 offset:20480
	ds_read_b128 v[148:151], v116 offset:22528
	ds_read_b128 v[152:155], v117
	ds_read_b128 v[156:159], v117 offset:2048
	ds_read_b128 v[160:163], v117 offset:4096
	ds_read_b128 v[164:167], v117 offset:6144
	ds_read_b128 v[168:171], v118 offset:16384
	ds_read_b128 v[176:179], v118 offset:18432
	ds_read_b128 v[180:183], v118 offset:20480
	ds_read_b128 v[184:187], v118 offset:22528
	s_waitcnt lgkmcnt(8)
	v_mfma_f32_16x16x32_f16 v[60:63], v[136:139], v[120:123], v[60:63]
	v_mfma_f32_16x16x32_f16 v[56:59], v[140:143], v[120:123], v[56:59]
	v_mfma_f32_16x16x32_f16 v[52:55], v[144:147], v[120:123], v[52:55]
	v_mfma_f32_16x16x32_f16 v[48:51], v[148:151], v[120:123], v[48:51]
	v_mfma_f32_16x16x32_f16 v[44:47], v[136:139], v[124:127], v[44:47]
	v_mfma_f32_16x16x32_f16 v[40:43], v[140:143], v[124:127], v[40:43]
	v_mfma_f32_16x16x32_f16 v[36:39], v[144:147], v[124:127], v[36:39]
	v_mfma_f32_16x16x32_f16 v[32:35], v[148:151], v[124:127], v[32:35]
	v_mfma_f32_16x16x32_f16 v[120:123], v[136:139], v[128:131], v[28:31]
	v_mfma_f32_16x16x32_f16 v[124:127], v[140:143], v[128:131], v[24:27]
	v_mfma_f32_16x16x32_f16 v[188:191], v[144:147], v[128:131], v[20:23]
	v_mfma_f32_16x16x32_f16 v[128:131], v[148:151], v[128:131], v[16:19]
	v_mfma_f32_16x16x32_f16 v[136:139], v[136:139], v[132:135], v[12:15]
	v_mfma_f32_16x16x32_f16 v[140:143], v[140:143], v[132:135], v[8:11]
	v_mfma_f32_16x16x32_f16 v[144:147], v[144:147], v[132:135], v[4:7]
	v_mfma_f32_16x16x32_f16 v[132:135], v[148:151], v[132:135], v[0:3]
	s_waitcnt lgkmcnt(0)
	v_mfma_f32_16x16x32_f16 v[0:3], v[168:171], v[152:155], v[60:63]
	v_mfma_f32_16x16x32_f16 v[4:7], v[176:179], v[152:155], v[56:59]
	v_mfma_f32_16x16x32_f16 v[8:11], v[180:183], v[152:155], v[52:55]
	v_mfma_f32_16x16x32_f16 v[12:15], v[184:187], v[152:155], v[48:51]
	v_mfma_f32_16x16x32_f16 v[16:19], v[168:171], v[156:159], v[44:47]
	v_mfma_f32_16x16x32_f16 v[20:23], v[176:179], v[156:159], v[40:43]
	v_mfma_f32_16x16x32_f16 v[24:27], v[180:183], v[156:159], v[36:39]
	v_mfma_f32_16x16x32_f16 v[28:31], v[184:187], v[156:159], v[32:35]
	v_mfma_f32_16x16x32_f16 v[32:35], v[168:171], v[160:163], v[120:123]
	v_mfma_f32_16x16x32_f16 v[36:39], v[176:179], v[160:163], v[124:127]
	v_mfma_f32_16x16x32_f16 v[40:43], v[180:183], v[160:163], v[188:191]
	v_mfma_f32_16x16x32_f16 v[44:47], v[184:187], v[160:163], v[128:131]
	v_mfma_f32_16x16x32_f16 v[48:51], v[168:171], v[164:167], v[136:139]
	v_mfma_f32_16x16x32_f16 v[52:55], v[176:179], v[164:167], v[140:143]
	v_mfma_f32_16x16x32_f16 v[56:59], v[180:183], v[164:167], v[144:147]
	v_mfma_f32_16x16x32_f16 v[60:63], v[184:187], v[164:167], v[132:135]
	s_waitcnt vmcnt(0)
	s_cmp_gt_u32 s11, 13
	s_cselect_b64 s[88:89], -1, 0
	s_and_b64 vcc, exec, s[88:89]
	s_waitcnt vmcnt(0)
	s_barrier
	s_cbranch_vccnz .LBB0_751
	s_mov_b32 m0, s100
	s_nop 0
	global_load_lds_dwordx4 v66, s[84:85]
	s_add_i32 m0, s100, 0x1000
	s_nop 0
	global_load_lds_dwordx4 v68, s[84:85]
	s_add_i32 m0, s100, 0x2000
	s_nop 0
	global_load_lds_dwordx4 v70, s[84:85]
	s_add_i32 m0, s100, 0x3000
	s_nop 0
	global_load_lds_dwordx4 v72, s[84:85]
	s_add_i32 m0, s100, 0x4000
	s_nop 0
	global_load_lds_dwordx4 v74, s[98:99]
	s_add_i32 m0, s100, 0x5000
	s_nop 0
	global_load_lds_dwordx4 v76, s[98:99]
	s_add_i32 m0, s100, 0x6000
	s_nop 0
	global_load_lds_dwordx4 v78, s[98:99]
	s_add_i32 m0, s100, 0x7000
	s_nop 0
	global_load_lds_dwordx4 v80, s[98:99]
	s_add_u32 s84, s84, 0x80
	s_addc_u32 s85, s85, 0
	s_add_u32 s98, s98, 0x80
	s_addc_u32 s99, s99, 0
	s_branch .LBB0_751

.LBB0_883:
	ds_read_b128 v[82:85], v115 offset:32768
	ds_read_b128 v[86:89], v115 offset:34816
	ds_read_b128 v[90:93], v115 offset:36864
	ds_read_b128 v[94:97], v115 offset:38912
	ds_read_b128 v[120:123], v116 offset:49152
	ds_read_b128 v[124:127], v116 offset:51200
	ds_read_b128 v[128:131], v116 offset:53248
	ds_read_b128 v[132:135], v116 offset:55296
	ds_read_b128 v[136:139], v117 offset:32768
	ds_read_b128 v[140:143], v117 offset:34816
	ds_read_b128 v[144:147], v117 offset:36864
	ds_read_b128 v[148:151], v117 offset:38912
	ds_read_b128 v[152:155], v118 offset:49152
	ds_read_b128 v[156:159], v118 offset:51200
	ds_read_b128 v[160:163], v118 offset:53248
	ds_read_b128 v[164:167], v118 offset:55296
	s_add_i32 s11, s11, 2
	s_waitcnt lgkmcnt(8)
	v_mfma_f32_16x16x32_f16 v[0:3], v[120:123], v[82:85], v[0:3]
	v_mfma_f32_16x16x32_f16 v[4:7], v[124:127], v[82:85], v[4:7]
	v_mfma_f32_16x16x32_f16 v[8:11], v[128:131], v[82:85], v[8:11]
	v_mfma_f32_16x16x32_f16 v[12:15], v[132:135], v[82:85], v[12:15]
	v_mfma_f32_16x16x32_f16 v[16:19], v[120:123], v[86:89], v[16:19]
	v_mfma_f32_16x16x32_f16 v[20:23], v[124:127], v[86:89], v[20:23]
	v_mfma_f32_16x16x32_f16 v[24:27], v[128:131], v[86:89], v[24:27]
	v_mfma_f32_16x16x32_f16 v[28:31], v[132:135], v[86:89], v[28:31]
	v_mfma_f32_16x16x32_f16 v[82:85], v[120:123], v[90:93], v[32:35]
	v_mfma_f32_16x16x32_f16 v[86:89], v[124:127], v[90:93], v[36:39]
	v_mfma_f32_16x16x32_f16 v[168:171], v[128:131], v[90:93], v[40:43]
	v_mfma_f32_16x16x32_f16 v[90:93], v[132:135], v[90:93], v[44:47]
	v_mfma_f32_16x16x32_f16 v[120:123], v[120:123], v[94:97], v[48:51]
	v_mfma_f32_16x16x32_f16 v[124:127], v[124:127], v[94:97], v[52:55]
	v_mfma_f32_16x16x32_f16 v[128:131], v[128:131], v[94:97], v[56:59]
	v_mfma_f32_16x16x32_f16 v[94:97], v[132:135], v[94:97], v[60:63]
	s_waitcnt lgkmcnt(0)
	v_mfma_f32_16x16x32_f16 v[60:63], v[152:155], v[136:139], v[0:3]
	v_mfma_f32_16x16x32_f16 v[52:55], v[156:159], v[136:139], v[4:7]
	v_mfma_f32_16x16x32_f16 v[56:59], v[160:163], v[136:139], v[8:11]
	v_mfma_f32_16x16x32_f16 v[48:51], v[164:167], v[136:139], v[12:15]
	v_mfma_f32_16x16x32_f16 v[44:47], v[152:155], v[140:143], v[16:19]
	v_mfma_f32_16x16x32_f16 v[36:39], v[156:159], v[140:143], v[20:23]
	v_mfma_f32_16x16x32_f16 v[40:43], v[160:163], v[140:143], v[24:27]
	v_mfma_f32_16x16x32_f16 v[32:35], v[164:167], v[140:143], v[28:31]
	v_mfma_f32_16x16x32_f16 v[28:31], v[152:155], v[144:147], v[82:85]
	v_mfma_f32_16x16x32_f16 v[20:23], v[156:159], v[144:147], v[86:89]
	v_mfma_f32_16x16x32_f16 v[24:27], v[160:163], v[144:147], v[168:171]
	v_mfma_f32_16x16x32_f16 v[16:19], v[164:167], v[144:147], v[90:93]
	v_mfma_f32_16x16x32_f16 v[12:15], v[152:155], v[148:151], v[120:123]
	v_mfma_f32_16x16x32_f16 v[4:7], v[156:159], v[148:151], v[124:127]
	v_mfma_f32_16x16x32_f16 v[8:11], v[160:163], v[148:151], v[128:131]
	v_mfma_f32_16x16x32_f16 v[0:3], v[164:167], v[148:151], v[94:97]
	s_andn2_b64 vcc, exec, s[88:89]
	s_cbranch_vccz .LBB0_881
.LBB0_884:
	s_waitcnt vmcnt(0)
	s_waitcnt vmcnt(0) lgkmcnt(0)
	s_barrier
	s_add_i32 m0, s100, 0x8000
	s_nop 0
	global_load_lds_dwordx4 v66, s[84:85]
	s_add_i32 m0, s100, 0x9000
	s_nop 0
	global_load_lds_dwordx4 v68, s[84:85]
	s_add_i32 m0, s100, 0xa000
	s_nop 0
	global_load_lds_dwordx4 v70, s[84:85]
	s_add_i32 m0, s100, 0xb000
	s_nop 0
	global_load_lds_dwordx4 v72, s[84:85]
	s_add_i32 m0, s100, 0xc000
	s_nop 0
	global_load_lds_dwordx4 v74, s[98:99]
	s_add_i32 m0, s100, 0xd000
	s_nop 0
	global_load_lds_dwordx4 v76, s[98:99]
	s_add_i32 m0, s100, 0xe000
	s_nop 0
	global_load_lds_dwordx4 v78, s[98:99]
	s_add_i32 m0, s100, 0xf000
	s_nop 0
	global_load_lds_dwordx4 v80, s[98:99]
	s_add_u32 s84, s84, 0x80
	s_addc_u32 s85, s85, 0
	s_add_u32 s98, s98, 0x80
	s_addc_u32 s99, s99, 0
	ds_read_b128 v[120:123], v115
	ds_read_b128 v[124:127], v115 offset:2048
	ds_read_b128 v[128:131], v115 offset:4096
	ds_read_b128 v[132:135], v115 offset:6144
	ds_read_b128 v[136:139], v116 offset:16384
	ds_read_b128 v[140:143], v116 offset:18432
	ds_read_b128 v[144:147], v116 offset:20480
	ds_read_b128 v[148:151], v116 offset:22528
	ds_read_b128 v[152:155], v117
	ds_read_b128 v[156:159], v117 offset:2048
	ds_read_b128 v[160:163], v117 offset:4096
	ds_read_b128 v[164:167], v117 offset:6144
	ds_read_b128 v[168:171], v118 offset:16384
	ds_read_b128 v[176:179], v118 offset:18432
	ds_read_b128 v[180:183], v118 offset:20480
	ds_read_b128 v[184:187], v118 offset:22528
	s_waitcnt lgkmcnt(8)
	v_mfma_f32_16x16x32_f16 v[60:63], v[136:139], v[120:123], v[60:63]
	v_mfma_f32_16x16x32_f16 v[52:55], v[140:143], v[120:123], v[52:55]
	v_mfma_f32_16x16x32_f16 v[56:59], v[144:147], v[120:123], v[56:59]
	v_mfma_f32_16x16x32_f16 v[48:51], v[148:151], v[120:123], v[48:51]
	v_mfma_f32_16x16x32_f16 v[44:47], v[136:139], v[124:127], v[44:47]
	v_mfma_f32_16x16x32_f16 v[36:39], v[140:143], v[124:127], v[36:39]
	v_mfma_f32_16x16x32_f16 v[40:43], v[144:147], v[124:127], v[40:43]
	v_mfma_f32_16x16x32_f16 v[32:35], v[148:151], v[124:127], v[32:35]
	v_mfma_f32_16x16x32_f16 v[120:123], v[136:139], v[128:131], v[28:31]
	v_mfma_f32_16x16x32_f16 v[124:127], v[140:143], v[128:131], v[20:23]
	v_mfma_f32_16x16x32_f16 v[188:191], v[144:147], v[128:131], v[24:27]
	v_mfma_f32_16x16x32_f16 v[128:131], v[148:151], v[128:131], v[16:19]
	v_mfma_f32_16x16x32_f16 v[136:139], v[136:139], v[132:135], v[12:15]
	v_mfma_f32_16x16x32_f16 v[140:143], v[140:143], v[132:135], v[4:7]
	v_mfma_f32_16x16x32_f16 v[144:147], v[144:147], v[132:135], v[8:11]
	v_mfma_f32_16x16x32_f16 v[132:135], v[148:151], v[132:135], v[0:3]
	s_waitcnt lgkmcnt(0)
	v_mfma_f32_16x16x32_f16 v[0:3], v[168:171], v[152:155], v[60:63]
	v_mfma_f32_16x16x32_f16 v[4:7], v[176:179], v[152:155], v[52:55]
	v_mfma_f32_16x16x32_f16 v[8:11], v[180:183], v[152:155], v[56:59]
	v_mfma_f32_16x16x32_f16 v[12:15], v[184:187], v[152:155], v[48:51]
	v_mfma_f32_16x16x32_f16 v[16:19], v[168:171], v[156:159], v[44:47]
	v_mfma_f32_16x16x32_f16 v[20:23], v[176:179], v[156:159], v[36:39]
	v_mfma_f32_16x16x32_f16 v[24:27], v[180:183], v[156:159], v[40:43]
	v_mfma_f32_16x16x32_f16 v[28:31], v[184:187], v[156:159], v[32:35]
	v_mfma_f32_16x16x32_f16 v[32:35], v[168:171], v[160:163], v[120:123]
	v_mfma_f32_16x16x32_f16 v[36:39], v[176:179], v[160:163], v[124:127]
	v_mfma_f32_16x16x32_f16 v[40:43], v[180:183], v[160:163], v[188:191]
	v_mfma_f32_16x16x32_f16 v[44:47], v[184:187], v[160:163], v[128:131]
	v_mfma_f32_16x16x32_f16 v[48:51], v[168:171], v[164:167], v[136:139]
	v_mfma_f32_16x16x32_f16 v[52:55], v[176:179], v[164:167], v[140:143]
	v_mfma_f32_16x16x32_f16 v[56:59], v[180:183], v[164:167], v[144:147]
	v_mfma_f32_16x16x32_f16 v[60:63], v[184:187], v[164:167], v[132:135]
	s_waitcnt vmcnt(0)
	s_cmp_gt_u32 s11, 13
	s_cselect_b64 s[88:89], -1, 0
	s_and_b64 vcc, exec, s[88:89]
	s_waitcnt vmcnt(0)
	s_barrier
	s_cbranch_vccnz .LBB0_883
	s_mov_b32 m0, s100
	s_nop 0
	global_load_lds_dwordx4 v66, s[84:85]
	s_add_i32 m0, s100, 0x1000
	s_nop 0
	global_load_lds_dwordx4 v68, s[84:85]
	s_add_i32 m0, s100, 0x2000
	s_nop 0
	global_load_lds_dwordx4 v70, s[84:85]
	s_add_i32 m0, s100, 0x3000
	s_nop 0
	global_load_lds_dwordx4 v72, s[84:85]
	s_add_i32 m0, s100, 0x4000
	s_nop 0
	global_load_lds_dwordx4 v74, s[98:99]
	s_add_i32 m0, s100, 0x5000
	s_nop 0
	global_load_lds_dwordx4 v76, s[98:99]
	s_add_i32 m0, s100, 0x6000
	s_nop 0
	global_load_lds_dwordx4 v78, s[98:99]
	s_add_i32 m0, s100, 0x7000
	s_nop 0
	global_load_lds_dwordx4 v80, s[98:99]
	s_add_u32 s84, s84, 0x80
	s_addc_u32 s85, s85, 0
	s_add_u32 s98, s98, 0x80
	s_addc_u32 s99, s99, 0
	s_branch .LBB0_883

.LBB0_952:
	ds_read_b128 v[82:85], v115 offset:32768
	ds_read_b128 v[86:89], v115 offset:34816
	ds_read_b128 v[90:93], v115 offset:36864
	ds_read_b128 v[94:97], v115 offset:38912
	ds_read_b128 v[120:123], v116 offset:49152
	ds_read_b128 v[124:127], v116 offset:51200
	ds_read_b128 v[128:131], v116 offset:53248
	ds_read_b128 v[132:135], v116 offset:55296
	ds_read_b128 v[136:139], v117 offset:32768
	ds_read_b128 v[140:143], v117 offset:34816
	ds_read_b128 v[144:147], v117 offset:36864
	ds_read_b128 v[148:151], v117 offset:38912
	ds_read_b128 v[152:155], v118 offset:49152
	ds_read_b128 v[156:159], v118 offset:51200
	ds_read_b128 v[160:163], v118 offset:53248
	ds_read_b128 v[164:167], v118 offset:55296
	s_add_i32 s93, s93, 2
	s_waitcnt lgkmcnt(8)
	v_mfma_f32_16x16x32_f16 v[0:3], v[120:123], v[82:85], v[0:3]
	v_mfma_f32_16x16x32_f16 v[4:7], v[124:127], v[82:85], v[4:7]
	v_mfma_f32_16x16x32_f16 v[8:11], v[128:131], v[82:85], v[8:11]
	v_mfma_f32_16x16x32_f16 v[12:15], v[132:135], v[82:85], v[12:15]
	v_mfma_f32_16x16x32_f16 v[16:19], v[120:123], v[86:89], v[16:19]
	v_mfma_f32_16x16x32_f16 v[20:23], v[124:127], v[86:89], v[20:23]
	v_mfma_f32_16x16x32_f16 v[24:27], v[128:131], v[86:89], v[24:27]
	v_mfma_f32_16x16x32_f16 v[28:31], v[132:135], v[86:89], v[28:31]
	v_mfma_f32_16x16x32_f16 v[82:85], v[120:123], v[90:93], v[32:35]
	v_mfma_f32_16x16x32_f16 v[86:89], v[124:127], v[90:93], v[36:39]
	v_mfma_f32_16x16x32_f16 v[168:171], v[128:131], v[90:93], v[40:43]
	v_mfma_f32_16x16x32_f16 v[90:93], v[132:135], v[90:93], v[44:47]
	v_mfma_f32_16x16x32_f16 v[120:123], v[120:123], v[94:97], v[48:51]
	v_mfma_f32_16x16x32_f16 v[124:127], v[124:127], v[94:97], v[52:55]
	v_mfma_f32_16x16x32_f16 v[128:131], v[128:131], v[94:97], v[56:59]
	v_mfma_f32_16x16x32_f16 v[94:97], v[132:135], v[94:97], v[60:63]
	s_waitcnt lgkmcnt(0)
	v_mfma_f32_16x16x32_f16 v[60:63], v[152:155], v[136:139], v[0:3]
	v_mfma_f32_16x16x32_f16 v[56:59], v[156:159], v[136:139], v[4:7]
	v_mfma_f32_16x16x32_f16 v[52:55], v[160:163], v[136:139], v[8:11]
	v_mfma_f32_16x16x32_f16 v[48:51], v[164:167], v[136:139], v[12:15]
	v_mfma_f32_16x16x32_f16 v[44:47], v[152:155], v[140:143], v[16:19]
	v_mfma_f32_16x16x32_f16 v[40:43], v[156:159], v[140:143], v[20:23]
	v_mfma_f32_16x16x32_f16 v[36:39], v[160:163], v[140:143], v[24:27]
	v_mfma_f32_16x16x32_f16 v[32:35], v[164:167], v[140:143], v[28:31]
	v_mfma_f32_16x16x32_f16 v[28:31], v[152:155], v[144:147], v[82:85]
	v_mfma_f32_16x16x32_f16 v[24:27], v[156:159], v[144:147], v[86:89]
	v_mfma_f32_16x16x32_f16 v[20:23], v[160:163], v[144:147], v[168:171]
	v_mfma_f32_16x16x32_f16 v[16:19], v[164:167], v[144:147], v[90:93]
	v_mfma_f32_16x16x32_f16 v[12:15], v[152:155], v[148:151], v[120:123]
	v_mfma_f32_16x16x32_f16 v[8:11], v[156:159], v[148:151], v[124:127]
	v_mfma_f32_16x16x32_f16 v[4:7], v[160:163], v[148:151], v[128:131]
	v_mfma_f32_16x16x32_f16 v[0:3], v[164:167], v[148:151], v[94:97]
	s_andn2_b64 vcc, exec, s[12:13]
	s_cbranch_vccz .LBB0_950
.LBB0_953:
	s_waitcnt vmcnt(0)
	s_waitcnt lgkmcnt(0)
	s_barrier
	s_add_i32 m0, s100, 0x8000
	s_nop 0
	global_load_lds_dwordx4 v66, s[10:11]
	s_add_i32 m0, s100, 0x9000
	s_nop 0
	global_load_lds_dwordx4 v68, s[10:11]
	s_add_i32 m0, s100, 0xa000
	s_nop 0
	global_load_lds_dwordx4 v70, s[10:11]
	s_add_i32 m0, s100, 0xb000
	s_nop 0
	global_load_lds_dwordx4 v72, s[10:11]
	s_add_i32 m0, s100, 0xc000
	s_nop 0
	global_load_lds_dwordx4 v74, s[98:99]
	s_add_i32 m0, s100, 0xd000
	s_nop 0
	global_load_lds_dwordx4 v76, s[98:99]
	s_add_i32 m0, s100, 0xe000
	s_nop 0
	global_load_lds_dwordx4 v78, s[98:99]
	s_add_i32 m0, s100, 0xf000
	s_nop 0
	global_load_lds_dwordx4 v80, s[98:99]
	s_add_u32 s10, s10, 0x80
	s_addc_u32 s11, s11, 0
	s_add_u32 s98, s98, 0x80
	s_addc_u32 s99, s99, 0
	ds_read_b128 v[120:123], v115
	ds_read_b128 v[124:127], v115 offset:2048
	ds_read_b128 v[128:131], v115 offset:4096
	ds_read_b128 v[132:135], v115 offset:6144
	ds_read_b128 v[136:139], v116 offset:16384
	ds_read_b128 v[140:143], v116 offset:18432
	ds_read_b128 v[144:147], v116 offset:20480
	ds_read_b128 v[148:151], v116 offset:22528
	ds_read_b128 v[152:155], v117
	ds_read_b128 v[156:159], v117 offset:2048
	ds_read_b128 v[160:163], v117 offset:4096
	ds_read_b128 v[164:167], v117 offset:6144
	ds_read_b128 v[168:171], v118 offset:16384
	ds_read_b128 v[176:179], v118 offset:18432
	ds_read_b128 v[180:183], v118 offset:20480
	ds_read_b128 v[184:187], v118 offset:22528
	s_waitcnt lgkmcnt(8)
	v_mfma_f32_16x16x32_f16 v[60:63], v[136:139], v[120:123], v[60:63]
	v_mfma_f32_16x16x32_f16 v[56:59], v[140:143], v[120:123], v[56:59]
	v_mfma_f32_16x16x32_f16 v[52:55], v[144:147], v[120:123], v[52:55]
	v_mfma_f32_16x16x32_f16 v[48:51], v[148:151], v[120:123], v[48:51]
	v_mfma_f32_16x16x32_f16 v[44:47], v[136:139], v[124:127], v[44:47]
	v_mfma_f32_16x16x32_f16 v[40:43], v[140:143], v[124:127], v[40:43]
	v_mfma_f32_16x16x32_f16 v[36:39], v[144:147], v[124:127], v[36:39]
	v_mfma_f32_16x16x32_f16 v[32:35], v[148:151], v[124:127], v[32:35]
	v_mfma_f32_16x16x32_f16 v[120:123], v[136:139], v[128:131], v[28:31]
	v_mfma_f32_16x16x32_f16 v[124:127], v[140:143], v[128:131], v[24:27]
	v_mfma_f32_16x16x32_f16 v[188:191], v[144:147], v[128:131], v[20:23]
	v_mfma_f32_16x16x32_f16 v[128:131], v[148:151], v[128:131], v[16:19]
	v_mfma_f32_16x16x32_f16 v[136:139], v[136:139], v[132:135], v[12:15]
	v_mfma_f32_16x16x32_f16 v[140:143], v[140:143], v[132:135], v[8:11]
	v_mfma_f32_16x16x32_f16 v[144:147], v[144:147], v[132:135], v[4:7]
	v_mfma_f32_16x16x32_f16 v[132:135], v[148:151], v[132:135], v[0:3]
	s_waitcnt lgkmcnt(0)
	v_mfma_f32_16x16x32_f16 v[0:3], v[168:171], v[152:155], v[60:63]
	v_mfma_f32_16x16x32_f16 v[4:7], v[176:179], v[152:155], v[56:59]
	v_mfma_f32_16x16x32_f16 v[8:11], v[180:183], v[152:155], v[52:55]
	v_mfma_f32_16x16x32_f16 v[12:15], v[184:187], v[152:155], v[48:51]
	v_mfma_f32_16x16x32_f16 v[16:19], v[168:171], v[156:159], v[44:47]
	v_mfma_f32_16x16x32_f16 v[20:23], v[176:179], v[156:159], v[40:43]
	v_mfma_f32_16x16x32_f16 v[24:27], v[180:183], v[156:159], v[36:39]
	v_mfma_f32_16x16x32_f16 v[28:31], v[184:187], v[156:159], v[32:35]
	v_mfma_f32_16x16x32_f16 v[32:35], v[168:171], v[160:163], v[120:123]
	v_mfma_f32_16x16x32_f16 v[36:39], v[176:179], v[160:163], v[124:127]
	v_mfma_f32_16x16x32_f16 v[40:43], v[180:183], v[160:163], v[188:191]
	v_mfma_f32_16x16x32_f16 v[44:47], v[184:187], v[160:163], v[128:131]
	v_mfma_f32_16x16x32_f16 v[48:51], v[168:171], v[164:167], v[136:139]
	v_mfma_f32_16x16x32_f16 v[52:55], v[176:179], v[164:167], v[140:143]
	v_mfma_f32_16x16x32_f16 v[56:59], v[180:183], v[164:167], v[144:147]
	v_mfma_f32_16x16x32_f16 v[60:63], v[184:187], v[164:167], v[132:135]
	s_waitcnt vmcnt(0)
	s_cmp_gt_u32 s93, 41
	s_cselect_b64 s[12:13], -1, 0
	s_and_b64 vcc, exec, s[12:13]
	s_waitcnt vmcnt(0)
	s_barrier
	s_cbranch_vccnz .LBB0_952
	s_mov_b32 m0, s100
	s_nop 0
	global_load_lds_dwordx4 v66, s[10:11]
	s_add_i32 m0, s100, 0x1000
	s_nop 0
	global_load_lds_dwordx4 v68, s[10:11]
	s_add_i32 m0, s100, 0x2000
	s_nop 0
	global_load_lds_dwordx4 v70, s[10:11]
	s_add_i32 m0, s100, 0x3000
	s_nop 0
	global_load_lds_dwordx4 v72, s[10:11]
	s_add_i32 m0, s100, 0x4000
	s_nop 0
	global_load_lds_dwordx4 v74, s[98:99]
	s_add_i32 m0, s100, 0x5000
	s_nop 0
	global_load_lds_dwordx4 v76, s[98:99]
	s_add_i32 m0, s100, 0x6000
	s_nop 0
	global_load_lds_dwordx4 v78, s[98:99]
	s_add_i32 m0, s100, 0x7000
	s_nop 0
	global_load_lds_dwordx4 v80, s[98:99]
	s_add_u32 s10, s10, 0x80
	s_addc_u32 s11, s11, 0
	s_add_u32 s98, s98, 0x80
	s_addc_u32 s99, s99, 0
	s_branch .LBB0_952

.LBB0_1592:
	ds_read_b128 v[82:85], v115 offset:32768
	ds_read_b128 v[86:89], v115 offset:34816
	ds_read_b128 v[90:93], v115 offset:36864
	ds_read_b128 v[94:97], v115 offset:38912
	ds_read_b128 v[120:123], v116 offset:49152
	ds_read_b128 v[124:127], v116 offset:51200
	ds_read_b128 v[128:131], v116 offset:53248
	ds_read_b128 v[132:135], v116 offset:55296
	ds_read_b128 v[136:139], v117 offset:32768
	ds_read_b128 v[140:143], v117 offset:34816
	ds_read_b128 v[144:147], v117 offset:36864
	ds_read_b128 v[148:151], v117 offset:38912
	ds_read_b128 v[152:155], v118 offset:49152
	ds_read_b128 v[156:159], v118 offset:51200
	ds_read_b128 v[160:163], v118 offset:53248
	ds_read_b128 v[164:167], v118 offset:55296
	s_add_i32 s11, s11, 2
	s_waitcnt lgkmcnt(8)
	v_mfma_f32_16x16x32_f16 v[0:3], v[120:123], v[82:85], v[0:3]
	v_mfma_f32_16x16x32_f16 v[4:7], v[124:127], v[82:85], v[4:7]
	v_mfma_f32_16x16x32_f16 v[8:11], v[128:131], v[82:85], v[8:11]
	v_mfma_f32_16x16x32_f16 v[12:15], v[132:135], v[82:85], v[12:15]
	v_mfma_f32_16x16x32_f16 v[16:19], v[120:123], v[86:89], v[16:19]
	v_mfma_f32_16x16x32_f16 v[20:23], v[124:127], v[86:89], v[20:23]
	v_mfma_f32_16x16x32_f16 v[24:27], v[128:131], v[86:89], v[24:27]
	v_mfma_f32_16x16x32_f16 v[28:31], v[132:135], v[86:89], v[28:31]
	v_mfma_f32_16x16x32_f16 v[82:85], v[120:123], v[90:93], v[32:35]
	v_mfma_f32_16x16x32_f16 v[86:89], v[124:127], v[90:93], v[36:39]
	v_mfma_f32_16x16x32_f16 v[168:171], v[128:131], v[90:93], v[40:43]
	v_mfma_f32_16x16x32_f16 v[90:93], v[132:135], v[90:93], v[44:47]
	v_mfma_f32_16x16x32_f16 v[120:123], v[120:123], v[94:97], v[48:51]
	v_mfma_f32_16x16x32_f16 v[124:127], v[124:127], v[94:97], v[52:55]
	v_mfma_f32_16x16x32_f16 v[128:131], v[128:131], v[94:97], v[56:59]
	v_mfma_f32_16x16x32_f16 v[94:97], v[132:135], v[94:97], v[60:63]
	s_waitcnt lgkmcnt(0)
	v_mfma_f32_16x16x32_f16 v[60:63], v[152:155], v[136:139], v[0:3]
	v_mfma_f32_16x16x32_f16 v[56:59], v[156:159], v[136:139], v[4:7]
	v_mfma_f32_16x16x32_f16 v[52:55], v[160:163], v[136:139], v[8:11]
	v_mfma_f32_16x16x32_f16 v[48:51], v[164:167], v[136:139], v[12:15]
	v_mfma_f32_16x16x32_f16 v[44:47], v[152:155], v[140:143], v[16:19]
	v_mfma_f32_16x16x32_f16 v[40:43], v[156:159], v[140:143], v[20:23]
	v_mfma_f32_16x16x32_f16 v[36:39], v[160:163], v[140:143], v[24:27]
	v_mfma_f32_16x16x32_f16 v[32:35], v[164:167], v[140:143], v[28:31]
	v_mfma_f32_16x16x32_f16 v[28:31], v[152:155], v[144:147], v[82:85]
	v_mfma_f32_16x16x32_f16 v[24:27], v[156:159], v[144:147], v[86:89]
	v_mfma_f32_16x16x32_f16 v[20:23], v[160:163], v[144:147], v[168:171]
	v_mfma_f32_16x16x32_f16 v[16:19], v[164:167], v[144:147], v[90:93]
	v_mfma_f32_16x16x32_f16 v[12:15], v[152:155], v[148:151], v[120:123]
	v_mfma_f32_16x16x32_f16 v[8:11], v[156:159], v[148:151], v[124:127]
	v_mfma_f32_16x16x32_f16 v[4:7], v[160:163], v[148:151], v[128:131]
	v_mfma_f32_16x16x32_f16 v[0:3], v[164:167], v[148:151], v[94:97]
	s_andn2_b64 vcc, exec, s[18:19]
	s_cbranch_vccz .LBB0_1590
.LBB0_1593:
	s_waitcnt vmcnt(0)
	s_waitcnt vmcnt(0) lgkmcnt(0)
	s_barrier
	s_add_i32 m0, s100, 0x8000
	s_nop 0
	global_load_lds_dwordx4 v66, s[16:17]
	s_add_i32 m0, s100, 0x9000
	s_nop 0
	global_load_lds_dwordx4 v68, s[16:17]
	s_add_i32 m0, s100, 0xa000
	s_nop 0
	global_load_lds_dwordx4 v70, s[16:17]
	s_add_i32 m0, s100, 0xb000
	s_nop 0
	global_load_lds_dwordx4 v72, s[16:17]
	s_add_i32 m0, s100, 0xc000
	s_nop 0
	global_load_lds_dwordx4 v74, s[98:99]
	s_add_i32 m0, s100, 0xd000
	s_nop 0
	global_load_lds_dwordx4 v76, s[98:99]
	s_add_i32 m0, s100, 0xe000
	s_nop 0
	global_load_lds_dwordx4 v78, s[98:99]
	s_add_i32 m0, s100, 0xf000
	s_nop 0
	global_load_lds_dwordx4 v80, s[98:99]
	s_add_u32 s16, s16, 0x80
	s_addc_u32 s17, s17, 0
	s_add_u32 s98, s98, 0x80
	s_addc_u32 s99, s99, 0
	ds_read_b128 v[120:123], v115
	ds_read_b128 v[124:127], v115 offset:2048
	ds_read_b128 v[128:131], v115 offset:4096
	ds_read_b128 v[132:135], v115 offset:6144
	ds_read_b128 v[136:139], v116 offset:16384
	ds_read_b128 v[140:143], v116 offset:18432
	ds_read_b128 v[144:147], v116 offset:20480
	ds_read_b128 v[148:151], v116 offset:22528
	ds_read_b128 v[152:155], v117
	ds_read_b128 v[156:159], v117 offset:2048
	ds_read_b128 v[160:163], v117 offset:4096
	ds_read_b128 v[164:167], v117 offset:6144
	ds_read_b128 v[168:171], v118 offset:16384
	ds_read_b128 v[176:179], v118 offset:18432
	ds_read_b128 v[180:183], v118 offset:20480
	ds_read_b128 v[184:187], v118 offset:22528
	s_waitcnt lgkmcnt(8)
	v_mfma_f32_16x16x32_f16 v[60:63], v[136:139], v[120:123], v[60:63]
	v_mfma_f32_16x16x32_f16 v[56:59], v[140:143], v[120:123], v[56:59]
	v_mfma_f32_16x16x32_f16 v[52:55], v[144:147], v[120:123], v[52:55]
	v_mfma_f32_16x16x32_f16 v[48:51], v[148:151], v[120:123], v[48:51]
	v_mfma_f32_16x16x32_f16 v[44:47], v[136:139], v[124:127], v[44:47]
	v_mfma_f32_16x16x32_f16 v[40:43], v[140:143], v[124:127], v[40:43]
	v_mfma_f32_16x16x32_f16 v[36:39], v[144:147], v[124:127], v[36:39]
	v_mfma_f32_16x16x32_f16 v[32:35], v[148:151], v[124:127], v[32:35]
	v_mfma_f32_16x16x32_f16 v[120:123], v[136:139], v[128:131], v[28:31]
	v_mfma_f32_16x16x32_f16 v[124:127], v[140:143], v[128:131], v[24:27]
	v_mfma_f32_16x16x32_f16 v[188:191], v[144:147], v[128:131], v[20:23]
	v_mfma_f32_16x16x32_f16 v[128:131], v[148:151], v[128:131], v[16:19]
	v_mfma_f32_16x16x32_f16 v[136:139], v[136:139], v[132:135], v[12:15]
	v_mfma_f32_16x16x32_f16 v[140:143], v[140:143], v[132:135], v[8:11]
	v_mfma_f32_16x16x32_f16 v[144:147], v[144:147], v[132:135], v[4:7]
	v_mfma_f32_16x16x32_f16 v[132:135], v[148:151], v[132:135], v[0:3]
	s_waitcnt lgkmcnt(0)
	v_mfma_f32_16x16x32_f16 v[0:3], v[168:171], v[152:155], v[60:63]
	v_mfma_f32_16x16x32_f16 v[4:7], v[176:179], v[152:155], v[56:59]
	v_mfma_f32_16x16x32_f16 v[8:11], v[180:183], v[152:155], v[52:55]
	v_mfma_f32_16x16x32_f16 v[12:15], v[184:187], v[152:155], v[48:51]
	v_mfma_f32_16x16x32_f16 v[16:19], v[168:171], v[156:159], v[44:47]
	v_mfma_f32_16x16x32_f16 v[20:23], v[176:179], v[156:159], v[40:43]
	v_mfma_f32_16x16x32_f16 v[24:27], v[180:183], v[156:159], v[36:39]
	v_mfma_f32_16x16x32_f16 v[28:31], v[184:187], v[156:159], v[32:35]
	v_mfma_f32_16x16x32_f16 v[32:35], v[168:171], v[160:163], v[120:123]
	v_mfma_f32_16x16x32_f16 v[36:39], v[176:179], v[160:163], v[124:127]
	v_mfma_f32_16x16x32_f16 v[40:43], v[180:183], v[160:163], v[188:191]
	v_mfma_f32_16x16x32_f16 v[44:47], v[184:187], v[160:163], v[128:131]
	v_mfma_f32_16x16x32_f16 v[48:51], v[168:171], v[164:167], v[136:139]
	v_mfma_f32_16x16x32_f16 v[52:55], v[176:179], v[164:167], v[140:143]
	v_mfma_f32_16x16x32_f16 v[56:59], v[180:183], v[164:167], v[144:147]
	v_mfma_f32_16x16x32_f16 v[60:63], v[184:187], v[164:167], v[132:135]
	s_waitcnt vmcnt(0)
	s_cmp_gt_u32 s11, 13
	s_cselect_b64 s[18:19], -1, 0
	s_and_b64 vcc, exec, s[18:19]
	s_waitcnt vmcnt(0)
	s_barrier
	s_cbranch_vccnz .LBB0_1592
	s_mov_b32 m0, s100
	s_nop 0
	global_load_lds_dwordx4 v66, s[16:17]
	s_add_i32 m0, s100, 0x1000
	s_nop 0
	global_load_lds_dwordx4 v68, s[16:17]
	s_add_i32 m0, s100, 0x2000
	s_nop 0
	global_load_lds_dwordx4 v70, s[16:17]
	s_add_i32 m0, s100, 0x3000
	s_nop 0
	global_load_lds_dwordx4 v72, s[16:17]
	s_add_i32 m0, s100, 0x4000
	s_nop 0
	global_load_lds_dwordx4 v74, s[98:99]
	s_add_i32 m0, s100, 0x5000
	s_nop 0
	global_load_lds_dwordx4 v76, s[98:99]
	s_add_i32 m0, s100, 0x6000
	s_nop 0
	global_load_lds_dwordx4 v78, s[98:99]
	s_add_i32 m0, s100, 0x7000
	s_nop 0
	global_load_lds_dwordx4 v80, s[98:99]
	s_add_u32 s16, s16, 0x80
	s_addc_u32 s17, s17, 0
	s_add_u32 s98, s98, 0x80
	s_addc_u32 s99, s99, 0
	s_branch .LBB0_1592

.LBB0_1735:
	s_waitcnt vmcnt(0)
	s_waitcnt lgkmcnt(0)
	s_barrier
	s_add_i32 m0, s100, 0x8000
	s_nop 0
	global_load_lds_dwordx4 v66, s[16:17]
	s_add_i32 m0, s100, 0x9000
	s_nop 0
	global_load_lds_dwordx4 v68, s[16:17]
	s_add_i32 m0, s100, 0xa000
	s_nop 0
	global_load_lds_dwordx4 v70, s[16:17]
	s_add_i32 m0, s100, 0xb000
	s_nop 0
	global_load_lds_dwordx4 v72, s[16:17]
	s_add_i32 m0, s100, 0xc000
	s_nop 0
	global_load_lds_dwordx4 v74, s[98:99]
	s_add_i32 m0, s100, 0xd000
	s_nop 0
	global_load_lds_dwordx4 v76, s[98:99]
	s_add_i32 m0, s100, 0xe000
	s_nop 0
	global_load_lds_dwordx4 v78, s[98:99]
	s_add_i32 m0, s100, 0xf000
	s_nop 0
	global_load_lds_dwordx4 v80, s[98:99]
	s_add_u32 s16, s16, 0x80
	s_addc_u32 s17, s17, 0
	s_add_u32 s98, s98, 0x80
	s_addc_u32 s99, s99, 0
	ds_read_b128 v[120:123], v115
	ds_read_b128 v[124:127], v115 offset:2048
	ds_read_b128 v[128:131], v115 offset:4096
	ds_read_b128 v[132:135], v115 offset:6144
	ds_read_b128 v[136:139], v116 offset:16384
	ds_read_b128 v[140:143], v116 offset:18432
	ds_read_b128 v[144:147], v116 offset:20480
	ds_read_b128 v[148:151], v116 offset:22528
	ds_read_b128 v[152:155], v117
	ds_read_b128 v[156:159], v117 offset:2048
	ds_read_b128 v[160:163], v117 offset:4096
	ds_read_b128 v[164:167], v117 offset:6144
	ds_read_b128 v[168:171], v118 offset:16384
	ds_read_b128 v[176:179], v118 offset:18432
	ds_read_b128 v[180:183], v118 offset:20480
	ds_read_b128 v[184:187], v118 offset:22528
	s_waitcnt lgkmcnt(8)
	v_mfma_f32_16x16x32_f16 v[60:63], v[136:139], v[120:123], v[60:63]
	v_mfma_f32_16x16x32_f16 v[56:59], v[140:143], v[120:123], v[56:59]
	v_mfma_f32_16x16x32_f16 v[52:55], v[144:147], v[120:123], v[52:55]
	v_mfma_f32_16x16x32_f16 v[48:51], v[148:151], v[120:123], v[48:51]
	v_mfma_f32_16x16x32_f16 v[44:47], v[136:139], v[124:127], v[44:47]
	v_mfma_f32_16x16x32_f16 v[40:43], v[140:143], v[124:127], v[40:43]
	v_mfma_f32_16x16x32_f16 v[36:39], v[144:147], v[124:127], v[36:39]
	v_mfma_f32_16x16x32_f16 v[32:35], v[148:151], v[124:127], v[32:35]
	v_mfma_f32_16x16x32_f16 v[120:123], v[136:139], v[128:131], v[28:31]
	v_mfma_f32_16x16x32_f16 v[124:127], v[140:143], v[128:131], v[24:27]
	v_mfma_f32_16x16x32_f16 v[188:191], v[144:147], v[128:131], v[20:23]
	v_mfma_f32_16x16x32_f16 v[128:131], v[148:151], v[128:131], v[16:19]
	v_mfma_f32_16x16x32_f16 v[136:139], v[136:139], v[132:135], v[12:15]
	v_mfma_f32_16x16x32_f16 v[140:143], v[140:143], v[132:135], v[8:11]
	v_mfma_f32_16x16x32_f16 v[144:147], v[144:147], v[132:135], v[4:7]
	v_mfma_f32_16x16x32_f16 v[132:135], v[148:151], v[132:135], v[0:3]
	s_waitcnt lgkmcnt(0)
	v_mfma_f32_16x16x32_f16 v[0:3], v[168:171], v[152:155], v[60:63]
	v_mfma_f32_16x16x32_f16 v[4:7], v[176:179], v[152:155], v[56:59]
	v_mfma_f32_16x16x32_f16 v[8:11], v[180:183], v[152:155], v[52:55]
	v_mfma_f32_16x16x32_f16 v[12:15], v[184:187], v[152:155], v[48:51]
	v_mfma_f32_16x16x32_f16 v[16:19], v[168:171], v[156:159], v[44:47]
	v_mfma_f32_16x16x32_f16 v[20:23], v[176:179], v[156:159], v[40:43]
	v_mfma_f32_16x16x32_f16 v[24:27], v[180:183], v[156:159], v[36:39]
	v_mfma_f32_16x16x32_f16 v[28:31], v[184:187], v[156:159], v[32:35]
	v_mfma_f32_16x16x32_f16 v[32:35], v[168:171], v[160:163], v[120:123]
	v_mfma_f32_16x16x32_f16 v[36:39], v[176:179], v[160:163], v[124:127]
	v_mfma_f32_16x16x32_f16 v[40:43], v[180:183], v[160:163], v[188:191]
	v_mfma_f32_16x16x32_f16 v[44:47], v[184:187], v[160:163], v[128:131]
	v_mfma_f32_16x16x32_f16 v[48:51], v[168:171], v[164:167], v[136:139]
	v_mfma_f32_16x16x32_f16 v[52:55], v[176:179], v[164:167], v[140:143]
	v_mfma_f32_16x16x32_f16 v[56:59], v[180:183], v[164:167], v[144:147]
	v_mfma_f32_16x16x32_f16 v[60:63], v[184:187], v[164:167], v[132:135]
	s_waitcnt vmcnt(0)
	s_cmp_gt_u32 s11, 13
	s_cselect_b64 s[18:19], -1, 0
	s_and_b64 vcc, exec, s[18:19]
	s_waitcnt vmcnt(0)
	s_barrier
	s_cbranch_vccnz .LBB0_1734
	s_mov_b32 m0, s100
	s_nop 0
	global_load_lds_dwordx4 v66, s[16:17]
	s_add_i32 m0, s100, 0x1000
	s_nop 0
	global_load_lds_dwordx4 v68, s[16:17]
	s_add_i32 m0, s100, 0x2000
	s_nop 0
	global_load_lds_dwordx4 v70, s[16:17]
	s_add_i32 m0, s100, 0x3000
	s_nop 0
	global_load_lds_dwordx4 v72, s[16:17]
	s_add_i32 m0, s100, 0x4000
	s_nop 0
	global_load_lds_dwordx4 v74, s[98:99]
	s_add_i32 m0, s100, 0x5000
	s_nop 0
	global_load_lds_dwordx4 v76, s[98:99]
	s_add_i32 m0, s100, 0x6000
	s_nop 0
	global_load_lds_dwordx4 v78, s[98:99]
	s_add_i32 m0, s100, 0x7000
	s_nop 0
	global_load_lds_dwordx4 v80, s[98:99]
	s_add_u32 s16, s16, 0x80
	s_addc_u32 s17, s17, 0
	s_add_u32 s98, s98, 0x80
	s_addc_u32 s99, s99, 0
	s_branch .LBB0_1734

.LBB0_1866:
	ds_read_b128 v[82:85], v115 offset:32768
	ds_read_b128 v[86:89], v115 offset:34816
	ds_read_b128 v[90:93], v115 offset:36864
	ds_read_b128 v[94:97], v115 offset:38912
	ds_read_b128 v[120:123], v116 offset:49152
	ds_read_b128 v[124:127], v116 offset:51200
	ds_read_b128 v[128:131], v116 offset:53248
	ds_read_b128 v[132:135], v116 offset:55296
	ds_read_b128 v[136:139], v117 offset:32768
	ds_read_b128 v[140:143], v117 offset:34816
	ds_read_b128 v[144:147], v117 offset:36864
	ds_read_b128 v[148:151], v117 offset:38912
	ds_read_b128 v[152:155], v118 offset:49152
	ds_read_b128 v[156:159], v118 offset:51200
	ds_read_b128 v[160:163], v118 offset:53248
	ds_read_b128 v[164:167], v118 offset:55296
	s_add_i32 s11, s11, 2
	s_waitcnt lgkmcnt(8)
	v_mfma_f32_16x16x32_f16 v[0:3], v[120:123], v[82:85], v[0:3]
	v_mfma_f32_16x16x32_f16 v[4:7], v[124:127], v[82:85], v[4:7]
	v_mfma_f32_16x16x32_f16 v[8:11], v[128:131], v[82:85], v[8:11]
	v_mfma_f32_16x16x32_f16 v[12:15], v[132:135], v[82:85], v[12:15]
	v_mfma_f32_16x16x32_f16 v[16:19], v[120:123], v[86:89], v[16:19]
	v_mfma_f32_16x16x32_f16 v[20:23], v[124:127], v[86:89], v[20:23]
	v_mfma_f32_16x16x32_f16 v[24:27], v[128:131], v[86:89], v[24:27]
	v_mfma_f32_16x16x32_f16 v[28:31], v[132:135], v[86:89], v[28:31]
	v_mfma_f32_16x16x32_f16 v[82:85], v[120:123], v[90:93], v[32:35]
	v_mfma_f32_16x16x32_f16 v[86:89], v[124:127], v[90:93], v[36:39]
	v_mfma_f32_16x16x32_f16 v[168:171], v[128:131], v[90:93], v[40:43]
	v_mfma_f32_16x16x32_f16 v[90:93], v[132:135], v[90:93], v[44:47]
	v_mfma_f32_16x16x32_f16 v[120:123], v[120:123], v[94:97], v[48:51]
	v_mfma_f32_16x16x32_f16 v[124:127], v[124:127], v[94:97], v[52:55]
	v_mfma_f32_16x16x32_f16 v[128:131], v[128:131], v[94:97], v[56:59]
	v_mfma_f32_16x16x32_f16 v[94:97], v[132:135], v[94:97], v[60:63]
	s_waitcnt lgkmcnt(0)
	v_mfma_f32_16x16x32_f16 v[60:63], v[152:155], v[136:139], v[0:3]
	v_mfma_f32_16x16x32_f16 v[52:55], v[156:159], v[136:139], v[4:7]
	v_mfma_f32_16x16x32_f16 v[56:59], v[160:163], v[136:139], v[8:11]
	v_mfma_f32_16x16x32_f16 v[48:51], v[164:167], v[136:139], v[12:15]
	v_mfma_f32_16x16x32_f16 v[44:47], v[152:155], v[140:143], v[16:19]
	v_mfma_f32_16x16x32_f16 v[36:39], v[156:159], v[140:143], v[20:23]
	v_mfma_f32_16x16x32_f16 v[40:43], v[160:163], v[140:143], v[24:27]
	v_mfma_f32_16x16x32_f16 v[32:35], v[164:167], v[140:143], v[28:31]
	v_mfma_f32_16x16x32_f16 v[28:31], v[152:155], v[144:147], v[82:85]
	v_mfma_f32_16x16x32_f16 v[20:23], v[156:159], v[144:147], v[86:89]
	v_mfma_f32_16x16x32_f16 v[24:27], v[160:163], v[144:147], v[168:171]
	v_mfma_f32_16x16x32_f16 v[16:19], v[164:167], v[144:147], v[90:93]
	v_mfma_f32_16x16x32_f16 v[12:15], v[152:155], v[148:151], v[120:123]
	v_mfma_f32_16x16x32_f16 v[4:7], v[156:159], v[148:151], v[124:127]
	v_mfma_f32_16x16x32_f16 v[8:11], v[160:163], v[148:151], v[128:131]
	v_mfma_f32_16x16x32_f16 v[0:3], v[164:167], v[148:151], v[94:97]
	s_andn2_b64 vcc, exec, s[18:19]
	s_cbranch_vccz .LBB0_1864
.LBB0_1867:
	s_waitcnt vmcnt(0)
	s_waitcnt vmcnt(0) lgkmcnt(0)
	s_barrier
	s_add_i32 m0, s100, 0x8000
	s_nop 0
	global_load_lds_dwordx4 v66, s[16:17]
	s_add_i32 m0, s100, 0x9000
	s_nop 0
	global_load_lds_dwordx4 v68, s[16:17]
	s_add_i32 m0, s100, 0xa000
	s_nop 0
	global_load_lds_dwordx4 v70, s[16:17]
	s_add_i32 m0, s100, 0xb000
	s_nop 0
	global_load_lds_dwordx4 v72, s[16:17]
	s_add_i32 m0, s100, 0xc000
	s_nop 0
	global_load_lds_dwordx4 v74, s[98:99]
	s_add_i32 m0, s100, 0xd000
	s_nop 0
	global_load_lds_dwordx4 v76, s[98:99]
	s_add_i32 m0, s100, 0xe000
	s_nop 0
	global_load_lds_dwordx4 v78, s[98:99]
	s_add_i32 m0, s100, 0xf000
	s_nop 0
	global_load_lds_dwordx4 v80, s[98:99]
	s_add_u32 s16, s16, 0x80
	s_addc_u32 s17, s17, 0
	s_add_u32 s98, s98, 0x80
	s_addc_u32 s99, s99, 0
	ds_read_b128 v[120:123], v115
	ds_read_b128 v[124:127], v115 offset:2048
	ds_read_b128 v[128:131], v115 offset:4096
	ds_read_b128 v[132:135], v115 offset:6144
	ds_read_b128 v[136:139], v116 offset:16384
	ds_read_b128 v[140:143], v116 offset:18432
	ds_read_b128 v[144:147], v116 offset:20480
	ds_read_b128 v[148:151], v116 offset:22528
	ds_read_b128 v[152:155], v117
	ds_read_b128 v[156:159], v117 offset:2048
	ds_read_b128 v[160:163], v117 offset:4096
	ds_read_b128 v[164:167], v117 offset:6144
	ds_read_b128 v[168:171], v118 offset:16384
	ds_read_b128 v[176:179], v118 offset:18432
	ds_read_b128 v[180:183], v118 offset:20480
	ds_read_b128 v[184:187], v118 offset:22528
	s_waitcnt lgkmcnt(8)
	v_mfma_f32_16x16x32_f16 v[60:63], v[136:139], v[120:123], v[60:63]
	v_mfma_f32_16x16x32_f16 v[52:55], v[140:143], v[120:123], v[52:55]
	v_mfma_f32_16x16x32_f16 v[56:59], v[144:147], v[120:123], v[56:59]
	v_mfma_f32_16x16x32_f16 v[48:51], v[148:151], v[120:123], v[48:51]
	v_mfma_f32_16x16x32_f16 v[44:47], v[136:139], v[124:127], v[44:47]
	v_mfma_f32_16x16x32_f16 v[36:39], v[140:143], v[124:127], v[36:39]
	v_mfma_f32_16x16x32_f16 v[40:43], v[144:147], v[124:127], v[40:43]
	v_mfma_f32_16x16x32_f16 v[32:35], v[148:151], v[124:127], v[32:35]
	v_mfma_f32_16x16x32_f16 v[120:123], v[136:139], v[128:131], v[28:31]
	v_mfma_f32_16x16x32_f16 v[124:127], v[140:143], v[128:131], v[20:23]
	v_mfma_f32_16x16x32_f16 v[188:191], v[144:147], v[128:131], v[24:27]
	v_mfma_f32_16x16x32_f16 v[128:131], v[148:151], v[128:131], v[16:19]
	v_mfma_f32_16x16x32_f16 v[136:139], v[136:139], v[132:135], v[12:15]
	v_mfma_f32_16x16x32_f16 v[140:143], v[140:143], v[132:135], v[4:7]
	v_mfma_f32_16x16x32_f16 v[144:147], v[144:147], v[132:135], v[8:11]
	v_mfma_f32_16x16x32_f16 v[132:135], v[148:151], v[132:135], v[0:3]
	s_waitcnt lgkmcnt(0)
	v_mfma_f32_16x16x32_f16 v[0:3], v[168:171], v[152:155], v[60:63]
	v_mfma_f32_16x16x32_f16 v[4:7], v[176:179], v[152:155], v[52:55]
	v_mfma_f32_16x16x32_f16 v[8:11], v[180:183], v[152:155], v[56:59]
	v_mfma_f32_16x16x32_f16 v[12:15], v[184:187], v[152:155], v[48:51]
	v_mfma_f32_16x16x32_f16 v[16:19], v[168:171], v[156:159], v[44:47]
	v_mfma_f32_16x16x32_f16 v[20:23], v[176:179], v[156:159], v[36:39]
	v_mfma_f32_16x16x32_f16 v[24:27], v[180:183], v[156:159], v[40:43]
	v_mfma_f32_16x16x32_f16 v[28:31], v[184:187], v[156:159], v[32:35]
	v_mfma_f32_16x16x32_f16 v[32:35], v[168:171], v[160:163], v[120:123]
	v_mfma_f32_16x16x32_f16 v[36:39], v[176:179], v[160:163], v[124:127]
	v_mfma_f32_16x16x32_f16 v[40:43], v[180:183], v[160:163], v[188:191]
	v_mfma_f32_16x16x32_f16 v[44:47], v[184:187], v[160:163], v[128:131]
	v_mfma_f32_16x16x32_f16 v[48:51], v[168:171], v[164:167], v[136:139]
	v_mfma_f32_16x16x32_f16 v[52:55], v[176:179], v[164:167], v[140:143]
	v_mfma_f32_16x16x32_f16 v[56:59], v[180:183], v[164:167], v[144:147]
	v_mfma_f32_16x16x32_f16 v[60:63], v[184:187], v[164:167], v[132:135]
	s_waitcnt vmcnt(0)
	s_cmp_gt_u32 s11, 13
	s_cselect_b64 s[18:19], -1, 0
	s_and_b64 vcc, exec, s[18:19]
	s_waitcnt vmcnt(0)
	s_barrier
	s_cbranch_vccnz .LBB0_1866
	s_mov_b32 m0, s100
	s_nop 0
	global_load_lds_dwordx4 v66, s[16:17]
	s_add_i32 m0, s100, 0x1000
	s_nop 0
	global_load_lds_dwordx4 v68, s[16:17]
	s_add_i32 m0, s100, 0x2000
	s_nop 0
	global_load_lds_dwordx4 v70, s[16:17]
	s_add_i32 m0, s100, 0x3000
	s_nop 0
	global_load_lds_dwordx4 v72, s[16:17]
	s_add_i32 m0, s100, 0x4000
	s_nop 0
	global_load_lds_dwordx4 v74, s[98:99]
	s_add_i32 m0, s100, 0x5000
	s_nop 0
	global_load_lds_dwordx4 v76, s[98:99]
	s_add_i32 m0, s100, 0x6000
	s_nop 0
	global_load_lds_dwordx4 v78, s[98:99]
	s_add_i32 m0, s100, 0x7000
	s_nop 0
	global_load_lds_dwordx4 v80, s[98:99]
	s_add_u32 s16, s16, 0x80
	s_addc_u32 s17, s17, 0
	s_add_u32 s98, s98, 0x80
	s_addc_u32 s99, s99, 0
	s_branch .LBB0_1866

.LBB0_1935:
	ds_read_b128 v[82:85], v115 offset:32768
	ds_read_b128 v[86:89], v115 offset:34816
	ds_read_b128 v[90:93], v115 offset:36864
	ds_read_b128 v[94:97], v115 offset:38912
	ds_read_b128 v[120:123], v116 offset:49152
	ds_read_b128 v[124:127], v116 offset:51200
	ds_read_b128 v[128:131], v116 offset:53248
	ds_read_b128 v[132:135], v116 offset:55296
	ds_read_b128 v[136:139], v117 offset:32768
	ds_read_b128 v[140:143], v117 offset:34816
	ds_read_b128 v[144:147], v117 offset:36864
	ds_read_b128 v[148:151], v117 offset:38912
	ds_read_b128 v[152:155], v118 offset:49152
	ds_read_b128 v[156:159], v118 offset:51200
	ds_read_b128 v[160:163], v118 offset:53248
	ds_read_b128 v[164:167], v118 offset:55296
	s_add_i32 s22, s22, 2
	s_waitcnt lgkmcnt(8)
	v_mfma_f32_16x16x32_f16 v[0:3], v[120:123], v[82:85], v[0:3]
	v_mfma_f32_16x16x32_f16 v[4:7], v[124:127], v[82:85], v[4:7]
	v_mfma_f32_16x16x32_f16 v[8:11], v[128:131], v[82:85], v[8:11]
	v_mfma_f32_16x16x32_f16 v[12:15], v[132:135], v[82:85], v[12:15]
	v_mfma_f32_16x16x32_f16 v[16:19], v[120:123], v[86:89], v[16:19]
	v_mfma_f32_16x16x32_f16 v[20:23], v[124:127], v[86:89], v[20:23]
	v_mfma_f32_16x16x32_f16 v[24:27], v[128:131], v[86:89], v[24:27]
	v_mfma_f32_16x16x32_f16 v[28:31], v[132:135], v[86:89], v[28:31]
	v_mfma_f32_16x16x32_f16 v[82:85], v[120:123], v[90:93], v[32:35]
	v_mfma_f32_16x16x32_f16 v[86:89], v[124:127], v[90:93], v[36:39]
	v_mfma_f32_16x16x32_f16 v[168:171], v[128:131], v[90:93], v[40:43]
	v_mfma_f32_16x16x32_f16 v[90:93], v[132:135], v[90:93], v[44:47]
	v_mfma_f32_16x16x32_f16 v[120:123], v[120:123], v[94:97], v[48:51]
	v_mfma_f32_16x16x32_f16 v[124:127], v[124:127], v[94:97], v[52:55]
	v_mfma_f32_16x16x32_f16 v[128:131], v[128:131], v[94:97], v[56:59]
	v_mfma_f32_16x16x32_f16 v[94:97], v[132:135], v[94:97], v[60:63]
	s_waitcnt lgkmcnt(0)
	v_mfma_f32_16x16x32_f16 v[60:63], v[152:155], v[136:139], v[0:3]
	v_mfma_f32_16x16x32_f16 v[56:59], v[156:159], v[136:139], v[4:7]
	v_mfma_f32_16x16x32_f16 v[52:55], v[160:163], v[136:139], v[8:11]
	v_mfma_f32_16x16x32_f16 v[48:51], v[164:167], v[136:139], v[12:15]
	v_mfma_f32_16x16x32_f16 v[44:47], v[152:155], v[140:143], v[16:19]
	v_mfma_f32_16x16x32_f16 v[40:43], v[156:159], v[140:143], v[20:23]
	v_mfma_f32_16x16x32_f16 v[36:39], v[160:163], v[140:143], v[24:27]
	v_mfma_f32_16x16x32_f16 v[32:35], v[164:167], v[140:143], v[28:31]
	v_mfma_f32_16x16x32_f16 v[28:31], v[152:155], v[144:147], v[82:85]
	v_mfma_f32_16x16x32_f16 v[24:27], v[156:159], v[144:147], v[86:89]
	v_mfma_f32_16x16x32_f16 v[20:23], v[160:163], v[144:147], v[168:171]
	v_mfma_f32_16x16x32_f16 v[16:19], v[164:167], v[144:147], v[90:93]
	v_mfma_f32_16x16x32_f16 v[12:15], v[152:155], v[148:151], v[120:123]
	v_mfma_f32_16x16x32_f16 v[8:11], v[156:159], v[148:151], v[124:127]
	v_mfma_f32_16x16x32_f16 v[4:7], v[160:163], v[148:151], v[128:131]
	v_mfma_f32_16x16x32_f16 v[0:3], v[164:167], v[148:151], v[94:97]
	s_andn2_b64 vcc, exec, s[10:11]
	s_cbranch_vccz .LBB0_1933
.LBB0_1936:
	s_waitcnt vmcnt(0)
	s_waitcnt lgkmcnt(0)
	s_barrier
	s_add_i32 m0, s100, 0x8000
	s_nop 0
	global_load_lds_dwordx4 v66, s[8:9]
	s_add_i32 m0, s100, 0x9000
	s_nop 0
	global_load_lds_dwordx4 v68, s[8:9]
	s_add_i32 m0, s100, 0xa000
	s_nop 0
	global_load_lds_dwordx4 v70, s[8:9]
	s_add_i32 m0, s100, 0xb000
	s_nop 0
	global_load_lds_dwordx4 v72, s[8:9]
	s_add_i32 m0, s100, 0xc000
	s_nop 0
	global_load_lds_dwordx4 v74, s[98:99]
	s_add_i32 m0, s100, 0xd000
	s_nop 0
	global_load_lds_dwordx4 v76, s[98:99]
	s_add_i32 m0, s100, 0xe000
	s_nop 0
	global_load_lds_dwordx4 v78, s[98:99]
	s_add_i32 m0, s100, 0xf000
	s_nop 0
	global_load_lds_dwordx4 v80, s[98:99]
	s_add_u32 s8, s8, 0x80
	s_addc_u32 s9, s9, 0
	s_add_u32 s98, s98, 0x80
	s_addc_u32 s99, s99, 0
	ds_read_b128 v[120:123], v115
	ds_read_b128 v[124:127], v115 offset:2048
	ds_read_b128 v[128:131], v115 offset:4096
	ds_read_b128 v[132:135], v115 offset:6144
	ds_read_b128 v[136:139], v116 offset:16384
	ds_read_b128 v[140:143], v116 offset:18432
	ds_read_b128 v[144:147], v116 offset:20480
	ds_read_b128 v[148:151], v116 offset:22528
	ds_read_b128 v[152:155], v117
	ds_read_b128 v[156:159], v117 offset:2048
	ds_read_b128 v[160:163], v117 offset:4096
	ds_read_b128 v[164:167], v117 offset:6144
	ds_read_b128 v[168:171], v118 offset:16384
	ds_read_b128 v[176:179], v118 offset:18432
	ds_read_b128 v[180:183], v118 offset:20480
	ds_read_b128 v[184:187], v118 offset:22528
	s_waitcnt lgkmcnt(8)
	v_mfma_f32_16x16x32_f16 v[60:63], v[136:139], v[120:123], v[60:63]
	v_mfma_f32_16x16x32_f16 v[56:59], v[140:143], v[120:123], v[56:59]
	v_mfma_f32_16x16x32_f16 v[52:55], v[144:147], v[120:123], v[52:55]
	v_mfma_f32_16x16x32_f16 v[48:51], v[148:151], v[120:123], v[48:51]
	v_mfma_f32_16x16x32_f16 v[44:47], v[136:139], v[124:127], v[44:47]
	v_mfma_f32_16x16x32_f16 v[40:43], v[140:143], v[124:127], v[40:43]
	v_mfma_f32_16x16x32_f16 v[36:39], v[144:147], v[124:127], v[36:39]
	v_mfma_f32_16x16x32_f16 v[32:35], v[148:151], v[124:127], v[32:35]
	v_mfma_f32_16x16x32_f16 v[120:123], v[136:139], v[128:131], v[28:31]
	v_mfma_f32_16x16x32_f16 v[124:127], v[140:143], v[128:131], v[24:27]
	v_mfma_f32_16x16x32_f16 v[188:191], v[144:147], v[128:131], v[20:23]
	v_mfma_f32_16x16x32_f16 v[128:131], v[148:151], v[128:131], v[16:19]
	v_mfma_f32_16x16x32_f16 v[136:139], v[136:139], v[132:135], v[12:15]
	v_mfma_f32_16x16x32_f16 v[140:143], v[140:143], v[132:135], v[8:11]
	v_mfma_f32_16x16x32_f16 v[144:147], v[144:147], v[132:135], v[4:7]
	v_mfma_f32_16x16x32_f16 v[132:135], v[148:151], v[132:135], v[0:3]
	s_waitcnt lgkmcnt(0)
	v_mfma_f32_16x16x32_f16 v[0:3], v[168:171], v[152:155], v[60:63]
	v_mfma_f32_16x16x32_f16 v[4:7], v[176:179], v[152:155], v[56:59]
	v_mfma_f32_16x16x32_f16 v[8:11], v[180:183], v[152:155], v[52:55]
	v_mfma_f32_16x16x32_f16 v[12:15], v[184:187], v[152:155], v[48:51]
	v_mfma_f32_16x16x32_f16 v[16:19], v[168:171], v[156:159], v[44:47]
	v_mfma_f32_16x16x32_f16 v[20:23], v[176:179], v[156:159], v[40:43]
	v_mfma_f32_16x16x32_f16 v[24:27], v[180:183], v[156:159], v[36:39]
	v_mfma_f32_16x16x32_f16 v[28:31], v[184:187], v[156:159], v[32:35]
	v_mfma_f32_16x16x32_f16 v[32:35], v[168:171], v[160:163], v[120:123]
	v_mfma_f32_16x16x32_f16 v[36:39], v[176:179], v[160:163], v[124:127]
	v_mfma_f32_16x16x32_f16 v[40:43], v[180:183], v[160:163], v[188:191]
	v_mfma_f32_16x16x32_f16 v[44:47], v[184:187], v[160:163], v[128:131]
	v_mfma_f32_16x16x32_f16 v[48:51], v[168:171], v[164:167], v[136:139]
	v_mfma_f32_16x16x32_f16 v[52:55], v[176:179], v[164:167], v[140:143]
	v_mfma_f32_16x16x32_f16 v[56:59], v[180:183], v[164:167], v[144:147]
	v_mfma_f32_16x16x32_f16 v[60:63], v[184:187], v[164:167], v[132:135]
	s_waitcnt vmcnt(0)
	s_cmp_gt_u32 s22, 41
	s_cselect_b64 s[10:11], -1, 0
	s_and_b64 vcc, exec, s[10:11]
	s_waitcnt vmcnt(0)
	s_barrier
	s_cbranch_vccnz .LBB0_1935
	s_mov_b32 m0, s100
	s_nop 0
	global_load_lds_dwordx4 v66, s[8:9]
	s_add_i32 m0, s100, 0x1000
	s_nop 0
	global_load_lds_dwordx4 v68, s[8:9]
	s_add_i32 m0, s100, 0x2000
	s_nop 0
	global_load_lds_dwordx4 v70, s[8:9]
	s_add_i32 m0, s100, 0x3000
	s_nop 0
	global_load_lds_dwordx4 v72, s[8:9]
	s_add_i32 m0, s100, 0x4000
	s_nop 0
	global_load_lds_dwordx4 v74, s[98:99]
	s_add_i32 m0, s100, 0x5000
	s_nop 0
	global_load_lds_dwordx4 v76, s[98:99]
	s_add_i32 m0, s100, 0x6000
	s_nop 0
	global_load_lds_dwordx4 v78, s[98:99]
	s_add_i32 m0, s100, 0x7000
	s_nop 0
	global_load_lds_dwordx4 v80, s[98:99]
	s_add_u32 s8, s8, 0x80
	s_addc_u32 s9, s9, 0
	s_add_u32 s98, s98, 0x80
	s_addc_u32 s99, s99, 0
	s_branch .LBB0_1935
